# accumulator re-initialisation between output tiles: 64 v_mov_b64 instead of 128 v_mov_b32
# speedup vs baseline: 1.0085x; 1.0035x over previous
.LBB0_65:
	s_add_u32 s0, s12, 0x80
	s_addc_u32 s1, s13, 0
	s_add_u32 s12, s10, 0x100
	s_addc_u32 s13, s11, 0
	s_mov_b32 s10, 0
	v_mov_b64_e32 v[2:3], 0
	v_mov_b64_e32 v[4:5], 0
	v_mov_b64_e32 v[6:7], 0
	v_mov_b64_e32 v[8:9], 0
	v_mov_b64_e32 v[10:11], 0
	v_mov_b64_e32 v[12:13], 0
	v_mov_b64_e32 v[14:15], 0
	v_mov_b64_e32 v[16:17], 0
	v_mov_b64_e32 v[18:19], 0
	v_mov_b64_e32 v[20:21], 0
	v_mov_b64_e32 v[22:23], 0
	v_mov_b64_e32 v[24:25], 0
	v_mov_b64_e32 v[26:27], 0
	v_mov_b64_e32 v[28:29], 0
	v_mov_b64_e32 v[30:31], 0
	v_mov_b64_e32 v[32:33], 0
	v_mov_b64_e32 v[34:35], 0
	v_mov_b64_e32 v[36:37], 0
	v_mov_b64_e32 v[38:39], 0
	v_mov_b64_e32 v[40:41], 0
	v_mov_b64_e32 v[42:43], 0
	v_mov_b64_e32 v[44:45], 0
	v_mov_b64_e32 v[46:47], 0
	v_mov_b64_e32 v[48:49], 0
	v_mov_b64_e32 v[50:51], 0
	v_mov_b64_e32 v[52:53], 0
	v_mov_b64_e32 v[54:55], 0
	v_mov_b64_e32 v[56:57], 0
	v_mov_b64_e32 v[58:59], 0
	v_mov_b64_e32 v[60:61], 0
	v_mov_b64_e32 v[62:63], 0
	v_mov_b64_e32 v[64:65], 0
	v_mov_b64_e32 v[66:67], 0
	v_mov_b64_e32 v[68:69], 0
	v_mov_b64_e32 v[70:71], 0
	v_mov_b64_e32 v[72:73], 0
	v_mov_b64_e32 v[74:75], 0
	v_mov_b64_e32 v[76:77], 0
	v_mov_b64_e32 v[78:79], 0
	v_mov_b64_e32 v[80:81], 0
	v_mov_b64_e32 v[82:83], 0
	v_mov_b64_e32 v[84:85], 0
	v_mov_b64_e32 v[86:87], 0
	v_mov_b64_e32 v[88:89], 0
	v_mov_b64_e32 v[90:91], 0
	v_mov_b64_e32 v[92:93], 0
	v_mov_b64_e32 v[94:95], 0
	v_mov_b64_e32 v[96:97], 0
	v_mov_b64_e32 v[98:99], 0
	v_mov_b64_e32 v[100:101], 0
	v_mov_b64_e32 v[102:103], 0
	v_mov_b64_e32 v[104:105], 0
	v_mov_b64_e32 v[106:107], 0
	v_mov_b64_e32 v[108:109], 0
	v_mov_b64_e32 v[110:111], 0
	v_mov_b64_e32 v[112:113], 0
	v_mov_b64_e32 v[114:115], 0
	v_mov_b64_e32 v[116:117], 0
	v_mov_b64_e32 v[118:119], 0
	v_mov_b64_e32 v[120:121], 0
	v_mov_b64_e32 v[122:123], 0
	v_mov_b64_e32 v[124:125], 0
	v_mov_b64_e32 v[126:127], 0
	v_mov_b64_e32 v[128:129], 0
